# remaining same-wave LDS write->read drains removed (weight transposes in P0/S5 phases, attention finalize), on top of the scalar-base stage loads
# baseline (speedup 1.0000x reference)
.LBB0_20:
	s_ashr_i32 s0, s16, 31
	s_lshr_b32 s0, s0, 26
	s_add_i32 s0, s16, s0
	s_ashr_i32 s11, s0, 6
	s_and_b32 s10, s0, 0xffffffc0
	s_lshl_b32 s17, s11, 11
	v_add_u32_e32 v22, s10, v4
	s_sub_i32 s0, s9, s17
	v_add_u32_e32 v24, 8, v22
	v_add_u32_e32 v26, 16, v22
	v_add_u32_e32 v28, 24, v22
	v_add_u32_e32 v30, 32, v22
	v_add_u32_e32 v32, 40, v22
	v_add_u32_e32 v34, 48, v22
	v_add_u32_e32 v36, 56, v22
	v_ashrrev_i32_e32 v23, 31, v22
	s_ashr_i32 s1, s0, 31
	v_ashrrev_i32_e32 v25, 31, v24
	v_ashrrev_i32_e32 v27, 31, v26
	v_ashrrev_i32_e32 v29, 31, v28
	v_ashrrev_i32_e32 v31, 31, v30
	v_ashrrev_i32_e32 v33, 31, v32
	v_ashrrev_i32_e32 v35, 31, v34
	v_ashrrev_i32_e32 v37, 31, v36
	v_lshlrev_b64 v[22:23], 13, v[22:23]
	v_lshl_add_u64 v[38:39], s[0:1], 2, v[0:1]
	v_lshlrev_b64 v[24:25], 13, v[24:25]
	v_lshlrev_b64 v[26:27], 13, v[26:27]
	v_lshlrev_b64 v[28:29], 13, v[28:29]
	v_lshlrev_b64 v[30:31], 13, v[30:31]
	v_lshlrev_b64 v[32:33], 13, v[32:33]
	v_lshlrev_b64 v[34:35], 13, v[34:35]
	v_lshlrev_b64 v[36:37], 13, v[36:37]
	v_lshl_add_u64 v[22:23], v[38:39], 0, v[22:23]
	v_lshl_add_u64 v[40:41], v[38:39], 0, v[24:25]
	v_lshl_add_u64 v[42:43], v[38:39], 0, v[26:27]
	v_lshl_add_u64 v[44:45], v[38:39], 0, v[28:29]
	v_lshl_add_u64 v[46:47], v[38:39], 0, v[30:31]
	v_lshl_add_u64 v[48:49], v[38:39], 0, v[32:33]
	v_lshl_add_u64 v[50:51], v[38:39], 0, v[34:35]
	v_lshl_add_u64 v[52:53], v[38:39], 0, v[36:37]
	global_load_dwordx4 v[22:25], v[22:23], off
	s_nop 0
	global_load_dwordx4 v[26:29], v[40:41], off
	global_load_dwordx4 v[30:33], v[42:43], off
	global_load_dwordx4 v[34:37], v[44:45], off
	s_nop 0
	global_load_dwordx4 v[38:41], v[46:47], off
	global_load_dwordx4 v[42:45], v[48:49], off
	s_nop 0
	global_load_dwordx4 v[46:49], v[50:51], off
	s_nop 0
	global_load_dwordx4 v[50:53], v[52:53], off
	s_lshl_b32 s1, s11, 8
	s_ashr_i32 s11, s10, 31
	s_sub_i32 s17, s13, s17
	s_sub_i32 s1, s14, s1
	v_lshl_add_u64 v[54:55], s[10:11], 1, v[2:3]
	s_and_b32 s10, s17, 0x700
	s_and_b32 s1, s1, 0xffffff80
	s_and_b32 s0, s0, 0x60
	s_add_i32 s10, s10, s1
	s_or_b32 s0, s10, s0
	v_add_u32_e32 v56, s0, v4
	v_add_u32_e32 v58, 8, v56
	v_add_u32_e32 v60, 16, v56
	v_add_u32_e32 v62, 24, v56
	v_ashrrev_i32_e32 v57, 31, v56
	v_ashrrev_i32_e32 v59, 31, v58
	v_ashrrev_i32_e32 v61, 31, v60
	v_ashrrev_i32_e32 v63, 31, v62
	v_lshlrev_b64 v[56:57], 11, v[56:57]
	v_lshlrev_b64 v[58:59], 11, v[58:59]
	v_lshlrev_b64 v[60:61], 11, v[60:61]
	v_lshlrev_b64 v[62:63], 11, v[62:63]
	v_lshl_add_u64 v[56:57], v[54:55], 0, v[56:57]
	v_lshl_add_u64 v[58:59], v[54:55], 0, v[58:59]
	v_lshl_add_u64 v[60:61], v[54:55], 0, v[60:61]
	v_lshl_add_u64 v[54:55], v[54:55], 0, v[62:63]
	s_add_i32 s16, s16, s6
	s_add_i32 s9, s9, s12
	s_add_i32 s13, s13, s8
	s_add_i32 s14, s14, s15
	s_cmpk_gt_i32 s16, 0x3ff
	s_waitcnt vmcnt(7)
	ds_write2_b32 v7, v22, v23 offset1:1
	ds_write2_b32 v7, v24, v25 offset0:2 offset1:3
	s_waitcnt vmcnt(6)
	ds_write2_b32 v8, v26, v27 offset1:1
	ds_write2_b32 v9, v28, v29 offset1:1
	s_waitcnt vmcnt(5)
	ds_write2_b32 v10, v30, v31 offset1:1
	ds_write2_b32 v11, v32, v33 offset1:1
	s_waitcnt vmcnt(4)
	ds_write2_b32 v12, v34, v35 offset1:1
	ds_write2_b32 v13, v36, v37 offset1:1
	s_waitcnt vmcnt(3)
	ds_write2_b32 v14, v38, v39 offset1:1
	ds_write2_b32 v15, v40, v41 offset1:1
	s_waitcnt vmcnt(2)
	ds_write2_b32 v16, v42, v43 offset1:1
	ds_write2_b32 v17, v44, v45 offset1:1
	s_waitcnt vmcnt(1)
	ds_write2_b32 v18, v46, v47 offset1:1
	ds_write2_b32 v19, v48, v49 offset1:1
	s_waitcnt vmcnt(0)
	ds_write2_b32 v20, v50, v51 offset1:1
	ds_write2_b32 v21, v52, v53 offset1:1
	ds_read2_b32 v[26:27], v6 offset0:33 offset1:41
	ds_read2_b32 v[28:29], v6 offset1:8
	ds_read2_b32 v[30:31], v6 offset0:66 offset1:74
	ds_read2_b32 v[32:33], v6 offset0:99 offset1:107
	ds_read2_b32 v[34:35], v6 offset0:132 offset1:140
	ds_read2_b32 v[36:37], v6 offset0:165 offset1:173
	ds_read2_b32 v[38:39], v6 offset0:198 offset1:206
	ds_read2_b32 v[40:41], v6 offset0:231 offset1:239
	ds_read2_b32 v[42:43], v6 offset0:49 offset1:57
	ds_read2_b32 v[44:45], v6 offset0:16 offset1:24
	ds_read2_b32 v[46:47], v6 offset0:82 offset1:90
	ds_read2_b32 v[48:49], v6 offset0:115 offset1:123
	ds_read2_b32 v[50:51], v6 offset0:148 offset1:156
	ds_read2_b32 v[52:53], v6 offset0:181 offset1:189
	ds_read2_b32 v[62:63], v6 offset0:214 offset1:222
	ds_read2_b32 v[64:65], v6 offset0:247 offset1:255
	s_waitcnt lgkmcnt(14)
	v_cvt_pk_bf16_f32 v22, v28, v26
	s_waitcnt lgkmcnt(12)
	v_cvt_pk_bf16_f32 v23, v30, v32
	s_waitcnt lgkmcnt(10)
	v_cvt_pk_bf16_f32 v24, v34, v36
	s_waitcnt lgkmcnt(8)
	v_cvt_pk_bf16_f32 v25, v38, v40
	v_cvt_pk_bf16_f32 v26, v29, v27
	v_cvt_pk_bf16_f32 v27, v31, v33
	v_cvt_pk_bf16_f32 v28, v35, v37
	v_cvt_pk_bf16_f32 v29, v39, v41
	s_waitcnt lgkmcnt(6)
	v_cvt_pk_bf16_f32 v30, v44, v42
	s_waitcnt lgkmcnt(4)
	v_cvt_pk_bf16_f32 v31, v46, v48
	s_waitcnt lgkmcnt(2)
	v_cvt_pk_bf16_f32 v32, v50, v52
	s_waitcnt lgkmcnt(0)
	v_cvt_pk_bf16_f32 v33, v62, v64
	v_cvt_pk_bf16_f32 v34, v45, v43
	v_cvt_pk_bf16_f32 v35, v47, v49
	v_cvt_pk_bf16_f32 v36, v51, v53
	v_cvt_pk_bf16_f32 v37, v63, v65
	global_store_dwordx4 v[56:57], v[22:25], off
	global_store_dwordx4 v[58:59], v[26:29], off
	global_store_dwordx4 v[60:61], v[30:33], off
	global_store_dwordx4 v[54:55], v[34:37], off
	s_cbranch_scc0 .LBB0_20

.LBB0_295:
	s_cmpk_gt_i32 s5, 0x1fff
	s_mov_b64 s[10:11], -1
	s_cbranch_scc0 .LBB0_317
	s_cmpk_gt_u32 s5, 0x3fff
	s_cbranch_scc0 .LBB0_310
	s_cmpk_gt_u32 s5, 0x43ff
	s_cbranch_scc0 .LBB0_307
	s_cmpk_gt_u32 s5, 0x4fff
	s_cbranch_scc0 .LBB0_304
	s_cmpk_gt_u32 s5, 0x5bff
	s_cbranch_scc0 .LBB0_301
	s_add_i32 s10, s5, 0xffffa400
	s_lshr_b32 s66, s10, 9
	s_lshl_b64 s[10:11], s[66:67], 22
	s_add_u32 s12, s50, s10
	s_addc_u32 s13, s51, s11
	s_lshl_b64 s[10:11], s[66:67], 21
	v_readlane_b32 s17, v252, 63
	s_add_u32 s17, s17, s10
	v_readlane_b32 s10, v253, 0
	s_addc_u32 s11, s10, s11
	s_lshl_b32 s10, s5, 1
	s_and_b32 s20, s10, 0x3c0
	s_lshl_b32 s10, s5, 5
	s_and_b32 s10, s10, 0x3e0
	s_lshl_b32 s21, s10, 2
	v_add_u32_e32 v30, s20, v10
	s_add_u32 s12, s12, s21
	s_addc_u32 s13, s13, 0
	v_ashrrev_i32_e32 v31, 31, v30
	v_lshl_add_u64 v[32:33], s[12:13], 0, v[152:153]
	v_lshlrev_b64 v[30:31], 12, v[30:31]
	v_lshl_add_u64 v[58:59], v[32:33], 0, v[30:31]
	s_mov_b32 s12, 0x8000
	v_add_co_u32_e32 v34, vcc, s12, v58
	s_mov_b32 s12, 0x10000
	s_nop 0
	v_addc_co_u32_e32 v35, vcc, 0, v59, vcc
	v_add_co_u32_e32 v38, vcc, s12, v58
	s_mov_b32 s12, 0x18000
	s_nop 0
	v_addc_co_u32_e32 v39, vcc, 0, v59, vcc
	v_add_co_u32_e32 v42, vcc, s12, v58
	s_mov_b32 s12, 0x28000
	s_nop 0
	v_addc_co_u32_e32 v43, vcc, 0, v59, vcc
	v_add_co_u32_e32 v46, vcc, s76, v58
	global_load_dwordx4 v[30:33], v[58:59], off
	s_nop 0
	global_load_dwordx4 v[34:37], v[34:35], off
	v_addc_co_u32_e32 v47, vcc, 0, v59, vcc
	v_add_co_u32_e32 v50, vcc, s12, v58
	global_load_dwordx4 v[38:41], v[38:39], off
	s_nop 0
	global_load_dwordx4 v[42:45], v[42:43], off
	v_addc_co_u32_e32 v51, vcc, 0, v59, vcc
	global_load_dwordx4 v[46:49], v[46:47], off
	s_nop 0
	global_load_dwordx4 v[50:53], v[50:51], off
	s_mov_b32 s12, 0x30000
	v_add_co_u32_e32 v54, vcc, s12, v58
	s_mov_b32 s12, 0x38000
	s_nop 0
	v_addc_co_u32_e32 v55, vcc, 0, v59, vcc
	global_load_dwordx4 v[54:57], v[54:55], off
	v_add_co_u32_e32 v58, vcc, s12, v58
	s_lshl_b32 s12, s20, 1
	s_nop 0
	v_addc_co_u32_e32 v59, vcc, 0, v59, vcc
	global_load_dwordx4 v[58:61], v[58:59], off
	v_add_u32_e32 v62, s10, v10
	s_add_u32 s12, s17, s12
	v_mov_b32_e32 v9, v153
	v_ashrrev_i32_e32 v63, 31, v62
	s_addc_u32 s13, s11, 0
	v_lshlrev_b64 v[62:63], 11, v[62:63]
	v_lshl_add_u64 v[66:67], s[12:13], 0, v[8:9]
	v_add_u32_e32 v64, s10, v11
	v_lshl_add_u64 v[62:63], v[66:67], 0, v[62:63]
	v_ashrrev_i32_e32 v65, 31, v64
	v_lshlrev_b64 v[64:65], 11, v[64:65]
	s_waitcnt vmcnt(7)
	ds_write2_b32 v15, v30, v31 offset1:1
	ds_write2_b32 v15, v32, v33 offset0:2 offset1:3
	s_waitcnt vmcnt(6)
	ds_write2_b32 v16, v34, v35 offset1:1
	ds_write2_b32 v17, v36, v37 offset1:1
	s_waitcnt vmcnt(5)
	ds_write2_b32 v18, v38, v39 offset1:1
	ds_write2_b32 v19, v40, v41 offset1:1
	s_waitcnt vmcnt(4)
	ds_write2_b32 v20, v42, v43 offset1:1
	ds_write2_b32 v21, v44, v45 offset1:1
	s_waitcnt vmcnt(3)
	ds_write2_b32 v22, v46, v47 offset1:1
	ds_write2_b32 v23, v48, v49 offset1:1
	s_waitcnt vmcnt(2)
	ds_write2_b32 v24, v50, v51 offset1:1
	ds_write2_b32 v25, v52, v53 offset1:1
	s_waitcnt vmcnt(1)
	ds_write2_b32 v26, v54, v55 offset1:1
	ds_write2_b32 v27, v56, v57 offset1:1
	s_waitcnt vmcnt(0)
	ds_write2_b32 v28, v58, v59 offset1:1
	ds_write2_b32 v29, v60, v61 offset1:1
	ds_read2_b32 v[34:35], v14 offset0:33 offset1:41
	ds_read2_b32 v[36:37], v14 offset1:8
	ds_read2_b32 v[38:39], v14 offset0:66 offset1:74
	ds_read2_b32 v[40:41], v14 offset0:99 offset1:107
	ds_read2_b32 v[42:43], v14 offset0:132 offset1:140
	ds_read2_b32 v[44:45], v14 offset0:165 offset1:173
	ds_read2_b32 v[46:47], v14 offset0:198 offset1:206
	ds_read2_b32 v[48:49], v14 offset0:231 offset1:239
	s_waitcnt lgkmcnt(6)
	v_cvt_pk_bf16_f32 v30, v36, v34
	s_waitcnt lgkmcnt(4)
	v_cvt_pk_bf16_f32 v31, v38, v40
	s_waitcnt lgkmcnt(2)
	v_cvt_pk_bf16_f32 v32, v42, v44
	v_cvt_pk_bf16_f32 v34, v37, v35
	s_waitcnt lgkmcnt(0)
	v_cvt_pk_bf16_f32 v33, v46, v48
	global_store_dwordx4 v[62:63], v[30:33], off
	v_cvt_pk_bf16_f32 v35, v39, v41
	v_cvt_pk_bf16_f32 v36, v43, v45
	v_cvt_pk_bf16_f32 v37, v47, v49
	ds_read2_b32 v[38:39], v14 offset0:49 offset1:57
	ds_read2_b32 v[40:41], v14 offset0:16 offset1:24
	ds_read2_b32 v[42:43], v14 offset0:82 offset1:90
	ds_read2_b32 v[44:45], v14 offset0:115 offset1:123
	ds_read2_b32 v[46:47], v14 offset0:148 offset1:156
	ds_read2_b32 v[48:49], v14 offset0:181 offset1:189
	ds_read2_b32 v[52:53], v14 offset0:214 offset1:222
	ds_read2_b32 v[54:55], v14 offset0:247 offset1:255
	v_lshl_add_u64 v[50:51], v[66:67], 0, v[64:65]
	global_store_dwordx4 v[50:51], v[34:37], off
	s_waitcnt lgkmcnt(6)
	v_cvt_pk_bf16_f32 v30, v40, v38
	s_waitcnt lgkmcnt(4)
	v_cvt_pk_bf16_f32 v31, v42, v44
	v_add_u32_e32 v34, s10, v12
	v_ashrrev_i32_e32 v35, 31, v34
	v_lshlrev_b64 v[34:35], 11, v[34:35]
	s_waitcnt lgkmcnt(2)
	v_cvt_pk_bf16_f32 v32, v46, v48
	s_waitcnt lgkmcnt(0)
	v_cvt_pk_bf16_f32 v33, v52, v54
	v_lshl_add_u64 v[34:35], v[66:67], 0, v[34:35]
	global_store_dwordx4 v[34:35], v[30:33], off
	v_add_u32_e32 v34, s10, v13
	v_ashrrev_i32_e32 v35, 31, v34
	v_lshlrev_b64 v[34:35], 11, v[34:35]
	v_cvt_pk_bf16_f32 v30, v41, v39
	v_cvt_pk_bf16_f32 v31, v43, v45
	v_cvt_pk_bf16_f32 v32, v47, v49
	v_cvt_pk_bf16_f32 v33, v53, v55
	v_lshl_add_u64 v[34:35], v[66:67], 0, v[34:35]
	global_store_dwordx4 v[34:35], v[30:33], off
	s_mov_b64 s[10:11], 0
.LBB0_301:
	s_andn2_b64 vcc, exec, s[10:11]
	s_cbranch_vccnz .LBB0_303
	s_add_i32 s10, s5, 0xffffb000
	s_cmpk_gt_u32 s10, 0x5ff
	s_cselect_b32 s11, 0xc00000, 0
	s_cselect_b32 s12, 0x600000, 0
	s_add_u32 s13, s48, s11
	s_addc_u32 s17, s49, 0
	v_readlane_b32 s11, v252, 61
	s_add_u32 s22, s11, s12
	v_readlane_b32 s11, v252, 62
	s_addc_u32 s23, s11, 0
	s_add_i32 s11, s5, 0xffffaa00
	s_cmpk_lt_u32 s10, 0x600
	s_cselect_b32 s10, s10, s11
	s_sext_i32_i16 s11, s10
	s_mulk_i32 s11, 0x2aab
	s_lshr_b32 s12, s11, 31
	s_ashr_i32 s11, s11, 20
	s_add_i32 s11, s11, s12
	s_sext_i32_i16 s12, s11
	s_mulk_i32 s11, 0x60
	s_sub_i32 s10, s10, s11
	s_sext_i32_i16 s10, s10
	s_lshl_b32 s10, s10, 5
	s_ashr_i32 s11, s10, 31
	s_lshl_b32 s12, s12, 6
	s_lshl_b64 s[20:21], s[10:11], 2
	s_add_u32 s20, s13, s20
	v_add_u32_e32 v9, s12, v10
	s_addc_u32 s21, s17, s21
	v_lshl_add_u64 v[58:59], s[20:21], 0, v[152:153]
	s_movk_i32 s11, 0x3000
	v_add_u32_e32 v32, 8, v9
	v_add_u32_e32 v38, 16, v9
	v_add_u32_e32 v40, 24, v9
	v_add_u32_e32 v46, 32, v9
	v_add_u32_e32 v48, 40, v9
	v_mad_i64_i32 v[30:31], s[20:21], v9, s11, v[58:59]
	v_mad_i64_i32 v[34:35], s[20:21], v32, s11, v[58:59]
	v_mad_i64_i32 v[38:39], s[20:21], v38, s11, v[58:59]
	v_mad_i64_i32 v[42:43], s[20:21], v40, s11, v[58:59]
	v_mad_i64_i32 v[46:47], s[20:21], v46, s11, v[58:59]
	v_mad_i64_i32 v[50:51], s[20:21], v48, s11, v[58:59]
	global_load_dwordx4 v[30:33], v[30:31], off
	s_nop 0
	global_load_dwordx4 v[34:37], v[34:35], off
	s_nop 0
	global_load_dwordx4 v[38:41], v[38:39], off
	s_nop 0
	global_load_dwordx4 v[42:45], v[42:43], off
	s_nop 0
	global_load_dwordx4 v[46:49], v[46:47], off
	s_nop 0
	global_load_dwordx4 v[50:53], v[50:51], off
	v_add_u32_e32 v54, 48, v9
	v_mad_i64_i32 v[54:55], s[20:21], v54, s11, v[58:59]
	global_load_dwordx4 v[54:57], v[54:55], off
	v_add_u32_e32 v9, 56, v9
	v_mad_i64_i32 v[58:59], s[20:21], v9, s11, v[58:59]
	global_load_dwordx4 v[58:61], v[58:59], off
	s_ashr_i32 s13, s12, 31
	s_lshl_b64 s[12:13], s[12:13], 1
	v_add_u32_e32 v62, s10, v10
	s_add_u32 s12, s22, s12
	v_mov_b32_e32 v9, v153
	v_ashrrev_i32_e32 v63, 31, v62
	s_addc_u32 s13, s23, s13
	v_lshlrev_b64 v[62:63], 11, v[62:63]
	v_lshl_add_u64 v[66:67], s[12:13], 0, v[8:9]
	v_add_u32_e32 v64, s10, v11
	v_lshl_add_u64 v[62:63], v[66:67], 0, v[62:63]
	v_ashrrev_i32_e32 v65, 31, v64
	v_lshlrev_b64 v[64:65], 11, v[64:65]
	v_lshl_add_u64 v[64:65], v[66:67], 0, v[64:65]
	s_waitcnt vmcnt(7)
	ds_write2_b32 v15, v30, v31 offset1:1
	ds_write2_b32 v15, v32, v33 offset0:2 offset1:3
	s_waitcnt vmcnt(6)
	ds_write2_b32 v16, v34, v35 offset1:1
	ds_write2_b32 v17, v36, v37 offset1:1
	s_waitcnt vmcnt(5)
	ds_write2_b32 v18, v38, v39 offset1:1
	ds_write2_b32 v19, v40, v41 offset1:1
	s_waitcnt vmcnt(4)
	ds_write2_b32 v20, v42, v43 offset1:1
	ds_write2_b32 v21, v44, v45 offset1:1
	s_waitcnt vmcnt(3)
	ds_write2_b32 v22, v46, v47 offset1:1
	ds_write2_b32 v23, v48, v49 offset1:1
	s_waitcnt vmcnt(2)
	ds_write2_b32 v24, v50, v51 offset1:1
	ds_write2_b32 v25, v52, v53 offset1:1
	s_waitcnt vmcnt(1)
	ds_write2_b32 v26, v54, v55 offset1:1
	ds_write2_b32 v27, v56, v57 offset1:1
	s_waitcnt vmcnt(0)
	ds_write2_b32 v28, v58, v59 offset1:1
	ds_write2_b32 v29, v60, v61 offset1:1
	ds_read2_b32 v[34:35], v14 offset0:33 offset1:41
	ds_read2_b32 v[36:37], v14 offset1:8
	ds_read2_b32 v[38:39], v14 offset0:66 offset1:74
	ds_read2_b32 v[40:41], v14 offset0:99 offset1:107
	ds_read2_b32 v[42:43], v14 offset0:132 offset1:140
	ds_read2_b32 v[44:45], v14 offset0:165 offset1:173
	ds_read2_b32 v[46:47], v14 offset0:198 offset1:206
	ds_read2_b32 v[48:49], v14 offset0:231 offset1:239
	ds_read2_b32 v[50:51], v14 offset0:49 offset1:57
	ds_read2_b32 v[52:53], v14 offset0:16 offset1:24
	ds_read2_b32 v[54:55], v14 offset0:82 offset1:90
	ds_read2_b32 v[56:57], v14 offset0:115 offset1:123
	ds_read2_b32 v[58:59], v14 offset0:148 offset1:156
	s_waitcnt lgkmcnt(11)
	v_cvt_pk_bf16_f32 v30, v36, v34
	s_waitcnt lgkmcnt(9)
	v_cvt_pk_bf16_f32 v31, v38, v40
	s_waitcnt lgkmcnt(7)
	v_cvt_pk_bf16_f32 v32, v42, v44
	s_waitcnt lgkmcnt(5)
	v_cvt_pk_bf16_f32 v33, v46, v48
	global_store_dwordx4 v[62:63], v[30:33], off
	v_cvt_pk_bf16_f32 v34, v37, v35
	v_cvt_pk_bf16_f32 v35, v39, v41
	v_cvt_pk_bf16_f32 v36, v43, v45
	ds_read2_b32 v[38:39], v14 offset0:181 offset1:189
	ds_read2_b32 v[40:41], v14 offset0:214 offset1:222
	ds_read2_b32 v[42:43], v14 offset0:247 offset1:255
	v_cvt_pk_bf16_f32 v37, v47, v49
	global_store_dwordx4 v[64:65], v[34:37], off
	s_waitcnt lgkmcnt(6)
	v_cvt_pk_bf16_f32 v30, v52, v50
	s_waitcnt lgkmcnt(4)
	v_cvt_pk_bf16_f32 v31, v54, v56
	v_add_u32_e32 v34, s10, v12
	v_ashrrev_i32_e32 v35, 31, v34
	v_lshlrev_b64 v[34:35], 11, v[34:35]
	s_waitcnt lgkmcnt(2)
	v_cvt_pk_bf16_f32 v32, v58, v38
	s_waitcnt lgkmcnt(0)
	v_cvt_pk_bf16_f32 v33, v40, v42
	v_lshl_add_u64 v[34:35], v[66:67], 0, v[34:35]
	global_store_dwordx4 v[34:35], v[30:33], off
	v_add_u32_e32 v34, s10, v13
	v_ashrrev_i32_e32 v35, 31, v34
	v_lshlrev_b64 v[34:35], 11, v[34:35]
	v_cvt_pk_bf16_f32 v30, v53, v51
	v_cvt_pk_bf16_f32 v31, v55, v57
	v_cvt_pk_bf16_f32 v32, v59, v39
	v_cvt_pk_bf16_f32 v33, v41, v43
	v_lshl_add_u64 v[34:35], v[66:67], 0, v[34:35]
	global_store_dwordx4 v[34:35], v[30:33], off

.LBB0_304:
	s_andn2_b64 vcc, exec, s[10:11]
	s_cbranch_vccnz .LBB0_306
	s_add_i32 s10, s5, 0xbc00
	s_and_b32 s11, s10, 0xffff
	s_mul_i32 s11, s11, 0xaaab
	s_lshr_b32 s12, s11, 23
	s_mul_i32 s11, s12, 0xc0
	s_sub_i32 s10, s10, s11
	s_lshl_b32 s10, s10, 5
	s_and_b32 s13, s10, 0xffe0
	v_lshl_add_u32 v9, s12, 6, v10
	s_lshl_b32 s66, s13, 2
	v_lshl_add_u64 v[58:59], v[0:1], 0, s[66:67]
	s_movk_i32 s14, 0x6000
	v_add_u32_e32 v32, 8, v9
	v_add_u32_e32 v38, 16, v9
	v_add_u32_e32 v40, 24, v9
	v_add_u32_e32 v46, 32, v9
	v_add_u32_e32 v48, 40, v9
	v_mad_i64_i32 v[30:31], s[10:11], v9, s14, v[58:59]
	v_mad_i64_i32 v[34:35], s[10:11], v32, s14, v[58:59]
	v_mad_i64_i32 v[38:39], s[10:11], v38, s14, v[58:59]
	v_mad_i64_i32 v[42:43], s[10:11], v40, s14, v[58:59]
	v_mad_i64_i32 v[46:47], s[10:11], v46, s14, v[58:59]
	v_mad_i64_i32 v[50:51], s[10:11], v48, s14, v[58:59]
	global_load_dwordx4 v[30:33], v[30:31], off
	s_nop 0
	global_load_dwordx4 v[34:37], v[34:35], off
	s_nop 0
	global_load_dwordx4 v[38:41], v[38:39], off
	s_nop 0
	global_load_dwordx4 v[42:45], v[42:43], off
	s_nop 0
	global_load_dwordx4 v[46:49], v[46:47], off
	s_nop 0
	global_load_dwordx4 v[50:53], v[50:51], off
	v_add_u32_e32 v54, 48, v9
	v_mad_i64_i32 v[54:55], s[10:11], v54, s14, v[58:59]
	global_load_dwordx4 v[54:57], v[54:55], off
	v_add_u32_e32 v9, 56, v9
	v_mad_i64_i32 v[58:59], s[10:11], v9, s14, v[58:59]
	global_load_dwordx4 v[58:61], v[58:59], off
	v_add_u32_e32 v62, s13, v10
	v_add_u32_e32 v64, s13, v11
	s_lshl_b32 s66, s12, 7
	v_ashrrev_i32_e32 v63, 31, v62
	v_ashrrev_i32_e32 v65, 31, v64
	v_lshl_add_u64 v[68:69], v[2:3], 0, s[66:67]
	v_lshlrev_b64 v[62:63], 11, v[62:63]
	v_add_u32_e32 v66, s13, v12
	v_lshlrev_b64 v[64:65], 11, v[64:65]
	v_lshl_add_u64 v[62:63], v[68:69], 0, v[62:63]
	v_lshl_add_u64 v[64:65], v[68:69], 0, v[64:65]
	v_ashrrev_i32_e32 v67, 31, v66
	s_waitcnt vmcnt(7)
	ds_write2_b32 v15, v30, v31 offset1:1
	ds_write2_b32 v15, v32, v33 offset0:2 offset1:3
	s_waitcnt vmcnt(6)
	ds_write2_b32 v16, v34, v35 offset1:1
	ds_write2_b32 v17, v36, v37 offset1:1
	s_waitcnt vmcnt(5)
	ds_write2_b32 v18, v38, v39 offset1:1
	ds_write2_b32 v19, v40, v41 offset1:1
	s_waitcnt vmcnt(4)
	ds_write2_b32 v20, v42, v43 offset1:1
	ds_write2_b32 v21, v44, v45 offset1:1
	s_waitcnt vmcnt(3)
	ds_write2_b32 v22, v46, v47 offset1:1
	ds_write2_b32 v23, v48, v49 offset1:1
	s_waitcnt vmcnt(2)
	ds_write2_b32 v24, v50, v51 offset1:1
	ds_write2_b32 v25, v52, v53 offset1:1
	s_waitcnt vmcnt(1)
	ds_write2_b32 v26, v54, v55 offset1:1
	ds_write2_b32 v27, v56, v57 offset1:1
	s_waitcnt vmcnt(0)
	ds_write2_b32 v28, v58, v59 offset1:1
	ds_write2_b32 v29, v60, v61 offset1:1
	ds_read2_b32 v[34:35], v14 offset0:33 offset1:41
	ds_read2_b32 v[36:37], v14 offset1:8
	ds_read2_b32 v[38:39], v14 offset0:66 offset1:74
	ds_read2_b32 v[40:41], v14 offset0:99 offset1:107
	ds_read2_b32 v[42:43], v14 offset0:132 offset1:140
	ds_read2_b32 v[44:45], v14 offset0:165 offset1:173
	ds_read2_b32 v[46:47], v14 offset0:198 offset1:206
	ds_read2_b32 v[48:49], v14 offset0:231 offset1:239
	ds_read2_b32 v[50:51], v14 offset0:49 offset1:57
	ds_read2_b32 v[52:53], v14 offset0:16 offset1:24
	ds_read2_b32 v[54:55], v14 offset0:82 offset1:90
	ds_read2_b32 v[56:57], v14 offset0:115 offset1:123
	ds_read2_b32 v[58:59], v14 offset0:148 offset1:156
	ds_read2_b32 v[60:61], v14 offset0:181 offset1:189
	ds_read2_b32 v[70:71], v14 offset0:214 offset1:222
	ds_read2_b32 v[72:73], v14 offset0:247 offset1:255
	s_waitcnt lgkmcnt(14)
	v_cvt_pk_bf16_f32 v30, v36, v34
	s_waitcnt lgkmcnt(12)
	v_cvt_pk_bf16_f32 v31, v38, v40
	s_waitcnt lgkmcnt(10)
	v_cvt_pk_bf16_f32 v32, v42, v44
	s_waitcnt lgkmcnt(8)
	v_cvt_pk_bf16_f32 v33, v46, v48
	v_cvt_pk_bf16_f32 v34, v37, v35
	v_cvt_pk_bf16_f32 v35, v39, v41
	v_cvt_pk_bf16_f32 v36, v43, v45
	v_cvt_pk_bf16_f32 v37, v47, v49
	global_store_dwordx4 v[62:63], v[30:33], off
	global_store_dwordx4 v[64:65], v[34:37], off
	s_waitcnt lgkmcnt(6)
	v_cvt_pk_bf16_f32 v38, v52, v50
	v_lshlrev_b64 v[30:31], 11, v[66:67]
	v_add_u32_e32 v34, s13, v13
	v_ashrrev_i32_e32 v35, 31, v34
	s_waitcnt lgkmcnt(4)
	v_cvt_pk_bf16_f32 v39, v54, v56
	s_waitcnt lgkmcnt(2)
	v_cvt_pk_bf16_f32 v40, v58, v60
	s_waitcnt lgkmcnt(0)
	v_cvt_pk_bf16_f32 v41, v70, v72
	v_lshl_add_u64 v[30:31], v[68:69], 0, v[30:31]
	v_lshlrev_b64 v[34:35], 11, v[34:35]
	global_store_dwordx4 v[30:31], v[38:41], off
	v_cvt_pk_bf16_f32 v30, v53, v51
	v_cvt_pk_bf16_f32 v31, v55, v57
	v_cvt_pk_bf16_f32 v32, v59, v61
	v_cvt_pk_bf16_f32 v33, v71, v73
	v_lshl_add_u64 v[34:35], v[68:69], 0, v[34:35]
	global_store_dwordx4 v[34:35], v[30:33], off

.LBB0_307:
	s_andn2_b64 vcc, exec, s[10:11]
	s_cbranch_vccnz .LBB0_309
	s_add_i32 s10, s5, 0xc000
	s_and_b32 s10, s10, 0xffc0
	v_add_u32_e32 v30, s10, v10
	s_lshl_b32 s11, s5, 7
	s_and_b32 s66, s11, 0x1f80
	v_ashrrev_i32_e32 v31, 31, v30
	v_lshl_add_u64 v[32:33], v[4:5], 0, s[66:67]
	v_lshlrev_b64 v[30:31], 13, v[30:31]
	v_lshl_add_u64 v[58:59], v[32:33], 0, v[30:31]
	v_add_co_u32_e32 v34, vcc, 0x10000, v58
	s_lshl_b32 s12, s5, 6
	s_nop 0
	v_addc_co_u32_e32 v35, vcc, 0, v59, vcc
	v_add_co_u32_e32 v38, vcc, 0x20000, v58
	global_load_dwordx4 v[30:33], v[58:59], off
	s_nop 0
	global_load_dwordx4 v[34:37], v[34:35], off
	v_addc_co_u32_e32 v39, vcc, 0, v59, vcc
	v_add_co_u32_e32 v42, vcc, 0x30000, v58
	s_lshl_b32 s13, s5, 2
	s_nop 0
	v_addc_co_u32_e32 v43, vcc, 0, v59, vcc
	v_add_co_u32_e32 v46, vcc, 0x40000, v58
	global_load_dwordx4 v[38:41], v[38:39], off
	s_nop 0
	global_load_dwordx4 v[42:45], v[42:43], off
	v_addc_co_u32_e32 v47, vcc, 0, v59, vcc
	v_add_co_u32_e32 v50, vcc, 0x50000, v58
	s_lshl_b32 s11, s5, 5
	s_nop 0
	v_addc_co_u32_e32 v51, vcc, 0, v59, vcc
	global_load_dwordx4 v[46:49], v[46:47], off
	s_nop 0
	global_load_dwordx4 v[50:53], v[50:51], off
	v_add_co_u32_e32 v54, vcc, 0x60000, v58
	s_and_b32 s12, s12, 0x700
	s_nop 0
	v_addc_co_u32_e32 v55, vcc, 0, v59, vcc
	global_load_dwordx4 v[54:57], v[54:55], off
	v_add_co_u32_e32 v58, vcc, 0x70000, v58
	s_and_b32 s13, s13, 0x80
	s_nop 0
	v_addc_co_u32_e32 v59, vcc, 0, v59, vcc
	global_load_dwordx4 v[58:61], v[58:59], off
	s_and_b32 s11, s11, 0x60
	s_or_b32 s12, s12, s13
	s_lshl_b32 s66, s10, 1
	s_or_b32 s10, s12, s11
	v_add_u32_e32 v64, s10, v10
	v_ashrrev_i32_e32 v65, 31, v64
	v_lshl_add_u64 v[62:63], v[6:7], 0, s[66:67]
	v_lshlrev_b64 v[64:65], 11, v[64:65]
	v_add_u32_e32 v66, s10, v11
	v_ashrrev_i32_e32 v67, 31, v66
	v_lshlrev_b64 v[66:67], 11, v[66:67]
	s_waitcnt vmcnt(7)
	ds_write2_b32 v15, v30, v31 offset1:1
	ds_write2_b32 v15, v32, v33 offset0:2 offset1:3
	s_waitcnt vmcnt(6)
	ds_write2_b32 v16, v34, v35 offset1:1
	ds_write2_b32 v17, v36, v37 offset1:1
	s_waitcnt vmcnt(5)
	ds_write2_b32 v18, v38, v39 offset1:1
	ds_write2_b32 v19, v40, v41 offset1:1
	s_waitcnt vmcnt(4)
	ds_write2_b32 v20, v42, v43 offset1:1
	ds_write2_b32 v21, v44, v45 offset1:1
	s_waitcnt vmcnt(3)
	ds_write2_b32 v22, v46, v47 offset1:1
	ds_write2_b32 v23, v48, v49 offset1:1
	s_waitcnt vmcnt(2)
	ds_write2_b32 v24, v50, v51 offset1:1
	ds_write2_b32 v25, v52, v53 offset1:1
	s_waitcnt vmcnt(1)
	ds_write2_b32 v26, v54, v55 offset1:1
	ds_write2_b32 v27, v56, v57 offset1:1
	s_waitcnt vmcnt(0)
	ds_write2_b32 v28, v58, v59 offset1:1
	ds_write2_b32 v29, v60, v61 offset1:1
	ds_read2_b32 v[34:35], v14 offset0:33 offset1:41
	ds_read2_b32 v[36:37], v14 offset1:8
	ds_read2_b32 v[38:39], v14 offset0:66 offset1:74
	ds_read2_b32 v[40:41], v14 offset0:99 offset1:107
	ds_read2_b32 v[42:43], v14 offset0:132 offset1:140
	ds_read2_b32 v[44:45], v14 offset0:165 offset1:173
	ds_read2_b32 v[46:47], v14 offset0:198 offset1:206
	ds_read2_b32 v[48:49], v14 offset0:231 offset1:239
	v_lshl_add_u64 v[50:51], v[62:63], 0, v[64:65]
	s_waitcnt lgkmcnt(6)
	v_cvt_pk_bf16_f32 v30, v36, v34
	s_waitcnt lgkmcnt(4)
	v_cvt_pk_bf16_f32 v31, v38, v40
	s_waitcnt lgkmcnt(2)
	v_cvt_pk_bf16_f32 v32, v42, v44
	s_waitcnt lgkmcnt(0)
	v_cvt_pk_bf16_f32 v33, v46, v48
	global_store_dwordx4 v[50:51], v[30:33], off
	v_cvt_pk_bf16_f32 v34, v37, v35
	v_cvt_pk_bf16_f32 v35, v39, v41
	v_cvt_pk_bf16_f32 v36, v43, v45
	v_cvt_pk_bf16_f32 v37, v47, v49
	ds_read2_b32 v[38:39], v14 offset0:49 offset1:57
	ds_read2_b32 v[40:41], v14 offset0:16 offset1:24
	ds_read2_b32 v[42:43], v14 offset0:82 offset1:90
	ds_read2_b32 v[44:45], v14 offset0:115 offset1:123
	ds_read2_b32 v[46:47], v14 offset0:148 offset1:156
	ds_read2_b32 v[48:49], v14 offset0:181 offset1:189
	ds_read2_b32 v[50:51], v14 offset0:214 offset1:222
	ds_read2_b32 v[52:53], v14 offset0:247 offset1:255
	v_lshl_add_u64 v[30:31], v[62:63], 0, v[66:67]
	global_store_dwordx4 v[30:31], v[34:37], off
	s_waitcnt lgkmcnt(6)
	v_cvt_pk_bf16_f32 v30, v40, v38
	s_waitcnt lgkmcnt(4)
	v_cvt_pk_bf16_f32 v31, v42, v44
	v_add_u32_e32 v34, s10, v12
	v_ashrrev_i32_e32 v35, 31, v34
	v_lshlrev_b64 v[34:35], 11, v[34:35]
	s_waitcnt lgkmcnt(2)
	v_cvt_pk_bf16_f32 v32, v46, v48
	s_waitcnt lgkmcnt(0)
	v_cvt_pk_bf16_f32 v33, v50, v52
	v_lshl_add_u64 v[34:35], v[62:63], 0, v[34:35]
	global_store_dwordx4 v[34:35], v[30:33], off
	v_add_u32_e32 v34, s10, v13
	v_ashrrev_i32_e32 v35, 31, v34
	v_lshlrev_b64 v[34:35], 11, v[34:35]
	v_cvt_pk_bf16_f32 v30, v41, v39
	v_cvt_pk_bf16_f32 v31, v43, v45
	v_cvt_pk_bf16_f32 v32, v47, v49
	v_cvt_pk_bf16_f32 v33, v51, v53
	v_lshl_add_u64 v[34:35], v[62:63], 0, v[34:35]
	global_store_dwordx4 v[34:35], v[30:33], off

.LBB0_315:
	s_lshl_b64 s[12:13], s[66:67], 24
	s_add_u32 s12, s54, s12
	s_addc_u32 s13, s55, s13
	s_add_u32 s17, s94, s10
	s_addc_u32 s11, s95, s11
	s_lshl_b32 s10, s5, 1
	s_and_b32 s20, s10, 0xfc0
	s_lshl_b32 s10, s5, 5
	s_and_b32 s10, s10, 0x3e0
	s_lshl_b32 s21, s10, 2
	v_add_u32_e32 v30, s20, v10
	s_add_u32 s12, s12, s21
	s_addc_u32 s13, s13, 0
	v_ashrrev_i32_e32 v31, 31, v30
	v_lshl_add_u64 v[32:33], s[12:13], 0, v[152:153]
	v_lshlrev_b64 v[30:31], 12, v[30:31]
	v_lshl_add_u64 v[58:59], v[32:33], 0, v[30:31]
	s_mov_b32 s12, 0x8000
	v_add_co_u32_e32 v34, vcc, s12, v58
	s_mov_b32 s12, 0x10000
	s_nop 0
	v_addc_co_u32_e32 v35, vcc, 0, v59, vcc
	v_add_co_u32_e32 v38, vcc, s12, v58
	s_mov_b32 s12, 0x18000
	s_nop 0
	v_addc_co_u32_e32 v39, vcc, 0, v59, vcc
	v_add_co_u32_e32 v42, vcc, s12, v58
	s_mov_b32 s12, 0x28000
	s_nop 0
	v_addc_co_u32_e32 v43, vcc, 0, v59, vcc
	v_add_co_u32_e32 v46, vcc, s76, v58
	global_load_dwordx4 v[30:33], v[58:59], off
	s_nop 0
	global_load_dwordx4 v[34:37], v[34:35], off
	v_addc_co_u32_e32 v47, vcc, 0, v59, vcc
	v_add_co_u32_e32 v50, vcc, s12, v58
	global_load_dwordx4 v[38:41], v[38:39], off
	s_nop 0
	global_load_dwordx4 v[42:45], v[42:43], off
	v_addc_co_u32_e32 v51, vcc, 0, v59, vcc
	global_load_dwordx4 v[46:49], v[46:47], off
	s_nop 0
	global_load_dwordx4 v[50:53], v[50:51], off
	s_mov_b32 s12, 0x30000
	v_add_co_u32_e32 v54, vcc, s12, v58
	s_mov_b32 s12, 0x38000
	s_nop 0
	v_addc_co_u32_e32 v55, vcc, 0, v59, vcc
	global_load_dwordx4 v[54:57], v[54:55], off
	v_add_co_u32_e32 v58, vcc, s12, v58
	s_lshl_b32 s12, s20, 1
	s_nop 0
	v_addc_co_u32_e32 v59, vcc, 0, v59, vcc
	global_load_dwordx4 v[58:61], v[58:59], off
	v_add_u32_e32 v62, s10, v10
	s_add_u32 s12, s17, s12
	v_mov_b32_e32 v9, v153
	v_ashrrev_i32_e32 v63, 31, v62
	s_addc_u32 s13, s11, 0
	v_lshlrev_b64 v[62:63], 13, v[62:63]
	v_lshl_add_u64 v[66:67], s[12:13], 0, v[8:9]
	v_add_u32_e32 v64, s10, v11
	v_lshl_add_u64 v[62:63], v[66:67], 0, v[62:63]
	v_ashrrev_i32_e32 v65, 31, v64
	v_lshlrev_b64 v[64:65], 13, v[64:65]
	v_lshl_add_u64 v[64:65], v[66:67], 0, v[64:65]
	s_waitcnt vmcnt(7)
	ds_write2_b32 v15, v30, v31 offset1:1
	ds_write2_b32 v15, v32, v33 offset0:2 offset1:3
	s_waitcnt vmcnt(6)
	ds_write2_b32 v16, v34, v35 offset1:1
	ds_write2_b32 v17, v36, v37 offset1:1
	s_waitcnt vmcnt(5)
	ds_write2_b32 v18, v38, v39 offset1:1
	ds_write2_b32 v19, v40, v41 offset1:1
	s_waitcnt vmcnt(4)
	ds_write2_b32 v20, v42, v43 offset1:1
	ds_write2_b32 v21, v44, v45 offset1:1
	s_waitcnt vmcnt(3)
	ds_write2_b32 v22, v46, v47 offset1:1
	ds_write2_b32 v23, v48, v49 offset1:1
	s_waitcnt vmcnt(2)
	ds_write2_b32 v24, v50, v51 offset1:1
	ds_write2_b32 v25, v52, v53 offset1:1
	s_waitcnt vmcnt(1)
	ds_write2_b32 v26, v54, v55 offset1:1
	ds_write2_b32 v27, v56, v57 offset1:1
	s_waitcnt vmcnt(0)
	ds_write2_b32 v28, v58, v59 offset1:1
	ds_write2_b32 v29, v60, v61 offset1:1
	ds_read2_b32 v[34:35], v14 offset0:33 offset1:41
	ds_read2_b32 v[36:37], v14 offset1:8
	ds_read2_b32 v[38:39], v14 offset0:66 offset1:74
	ds_read2_b32 v[40:41], v14 offset0:99 offset1:107
	ds_read2_b32 v[42:43], v14 offset0:132 offset1:140
	ds_read2_b32 v[44:45], v14 offset0:165 offset1:173
	ds_read2_b32 v[46:47], v14 offset0:198 offset1:206
	ds_read2_b32 v[48:49], v14 offset0:231 offset1:239
	ds_read2_b32 v[50:51], v14 offset0:49 offset1:57
	s_waitcnt lgkmcnt(7)
	v_cvt_pk_bf16_f32 v30, v36, v34
	s_waitcnt lgkmcnt(5)
	v_cvt_pk_bf16_f32 v31, v38, v40
	s_waitcnt lgkmcnt(3)
	v_cvt_pk_bf16_f32 v32, v42, v44
	s_waitcnt lgkmcnt(1)
	v_cvt_pk_bf16_f32 v33, v46, v48
	global_store_dwordx4 v[62:63], v[30:33], off
	v_cvt_pk_bf16_f32 v34, v37, v35
	v_cvt_pk_bf16_f32 v35, v39, v41
	v_cvt_pk_bf16_f32 v36, v43, v45
	v_cvt_pk_bf16_f32 v37, v47, v49
	ds_read2_b32 v[38:39], v14 offset0:16 offset1:24
	ds_read2_b32 v[40:41], v14 offset0:82 offset1:90
	ds_read2_b32 v[42:43], v14 offset0:115 offset1:123
	ds_read2_b32 v[44:45], v14 offset0:148 offset1:156
	ds_read2_b32 v[46:47], v14 offset0:181 offset1:189
	ds_read2_b32 v[48:49], v14 offset0:214 offset1:222
	ds_read2_b32 v[52:53], v14 offset0:247 offset1:255
	global_store_dwordx4 v[64:65], v[34:37], off
	s_waitcnt lgkmcnt(6)
	v_cvt_pk_bf16_f32 v30, v38, v50
	s_waitcnt lgkmcnt(4)
	v_cvt_pk_bf16_f32 v31, v40, v42
	v_add_u32_e32 v34, s10, v12
	v_ashrrev_i32_e32 v35, 31, v34
	v_lshlrev_b64 v[34:35], 13, v[34:35]
	s_waitcnt lgkmcnt(2)
	v_cvt_pk_bf16_f32 v32, v44, v46
	s_waitcnt lgkmcnt(0)
	v_cvt_pk_bf16_f32 v33, v48, v52
	v_lshl_add_u64 v[34:35], v[66:67], 0, v[34:35]
	global_store_dwordx4 v[34:35], v[30:33], off
	v_add_u32_e32 v34, s10, v13
	v_ashrrev_i32_e32 v35, 31, v34
	v_lshlrev_b64 v[34:35], 13, v[34:35]
	v_cvt_pk_bf16_f32 v30, v39, v51
	v_cvt_pk_bf16_f32 v31, v41, v43
	v_cvt_pk_bf16_f32 v32, v45, v47
	v_cvt_pk_bf16_f32 v33, v49, v53
	v_lshl_add_u64 v[34:35], v[66:67], 0, v[34:35]
	global_store_dwordx4 v[34:35], v[30:33], off

.LBB0_317:
	s_andn2_b64 vcc, exec, s[10:11]
	s_cbranch_vccnz .LBB0_280
	s_ashr_i32 s10, s5, 31
	s_lshr_b32 s10, s10, 21
	s_add_i32 s17, s5, s10
	s_ashr_i32 s10, s17, 11
	s_ashr_i32 s11, s10, 31
	s_lshl_b64 s[12:13], s[10:11], 24
	s_add_u32 s22, s52, s12
	s_addc_u32 s13, s53, s13
	s_add_i32 s12, s10, -2
	s_cmpk_lt_i32 s5, 0x1000
	s_cselect_b32 s11, s11, 0
	s_cselect_b32 s10, s10, s12
	s_mov_b32 s12, 0x5400000
	s_cselect_b32 s12, s12, 0x2c00000
	s_lshl_b64 s[10:11], s[10:11], 23
	s_add_u32 s10, s94, s10
	s_addc_u32 s11, s95, s11
	s_add_u32 s23, s10, s12
	s_addc_u32 s24, s11, 0
	s_and_b32 s10, s17, 0xf800
	s_sub_i32 s5, s5, s10
	s_sext_i32_i16 s10, s5
	s_bfe_u32 s10, s10, 0x70018
	s_add_i32 s10, s5, s10
	s_sext_i32_i16 s11, s10
	s_and_b32 s10, s10, 0xff80
	s_sub_i32 s5, s5, s10
	s_sext_i32_i16 s5, s5
	s_ashr_i32 s11, s11, 7
	s_lshl_b32 s10, s5, 5
	s_lshl_b32 s12, s11, 6
	s_ashr_i32 s11, s10, 31
	s_lshl_b64 s[20:21], s[10:11], 2
	v_add_u32_e32 v30, s12, v10
	s_add_u32 s20, s22, s20
	s_addc_u32 s21, s13, s21
	v_ashrrev_i32_e32 v31, 31, v30
	v_lshl_add_u64 v[32:33], s[20:21], 0, v[152:153]
	v_lshlrev_b64 v[30:31], 14, v[30:31]
	v_lshl_add_u64 v[58:59], v[32:33], 0, v[30:31]
	v_add_co_u32_e32 v34, vcc, s76, v58
	s_mov_b32 s5, 0x40000
	s_nop 0
	v_addc_co_u32_e32 v35, vcc, 0, v59, vcc
	v_add_co_u32_e32 v38, vcc, s5, v58
	s_mov_b32 s5, 0x60000
	s_nop 0
	v_addc_co_u32_e32 v39, vcc, 0, v59, vcc
	v_add_co_u32_e32 v42, vcc, s5, v58
	s_mov_b32 s5, 0x80000
	s_nop 0
	v_addc_co_u32_e32 v43, vcc, 0, v59, vcc
	v_add_co_u32_e32 v46, vcc, s5, v58
	s_mov_b32 s5, 0xa0000
	s_nop 0
	v_addc_co_u32_e32 v47, vcc, 0, v59, vcc
	v_add_co_u32_e32 v50, vcc, s5, v58
	global_load_dwordx4 v[30:33], v[58:59], off
	s_nop 0
	global_load_dwordx4 v[34:37], v[34:35], off
	v_addc_co_u32_e32 v51, vcc, 0, v59, vcc
	global_load_dwordx4 v[38:41], v[38:39], off
	s_nop 0
	global_load_dwordx4 v[42:45], v[42:43], off
	s_nop 0
	global_load_dwordx4 v[46:49], v[46:47], off
	s_nop 0
	global_load_dwordx4 v[50:53], v[50:51], off
	s_mov_b32 s5, 0xc0000
	v_add_co_u32_e32 v54, vcc, s5, v58
	s_mov_b32 s5, 0xe0000
	s_nop 0
	v_addc_co_u32_e32 v55, vcc, 0, v59, vcc
	global_load_dwordx4 v[54:57], v[54:55], off
	v_add_co_u32_e32 v58, vcc, s5, v58
	s_ashr_i32 s13, s12, 31
	s_nop 0
	v_addc_co_u32_e32 v59, vcc, 0, v59, vcc
	global_load_dwordx4 v[58:61], v[58:59], off
	s_lshl_b64 s[12:13], s[12:13], 1
	v_add_u32_e32 v62, s10, v10
	s_add_u32 s12, s23, s12
	v_mov_b32_e32 v9, v153
	v_ashrrev_i32_e32 v63, 31, v62
	s_addc_u32 s13, s24, s13
	v_lshlrev_b64 v[62:63], 11, v[62:63]
	v_lshl_add_u64 v[64:65], s[12:13], 0, v[8:9]
	s_waitcnt vmcnt(7)
	ds_write2_b32 v15, v30, v31 offset1:1
	ds_write2_b32 v15, v32, v33 offset0:2 offset1:3
	s_waitcnt vmcnt(6)
	ds_write2_b32 v16, v34, v35 offset1:1
	ds_write2_b32 v17, v36, v37 offset1:1
	s_waitcnt vmcnt(5)
	ds_write2_b32 v18, v38, v39 offset1:1
	ds_write2_b32 v19, v40, v41 offset1:1
	s_waitcnt vmcnt(4)
	ds_write2_b32 v20, v42, v43 offset1:1
	ds_write2_b32 v21, v44, v45 offset1:1
	s_waitcnt vmcnt(3)
	ds_write2_b32 v22, v46, v47 offset1:1
	ds_write2_b32 v23, v48, v49 offset1:1
	s_waitcnt vmcnt(2)
	ds_write2_b32 v24, v50, v51 offset1:1
	ds_write2_b32 v25, v52, v53 offset1:1
	s_waitcnt vmcnt(1)
	ds_write2_b32 v26, v54, v55 offset1:1
	ds_write2_b32 v27, v56, v57 offset1:1
	s_waitcnt vmcnt(0)
	ds_write2_b32 v28, v58, v59 offset1:1
	ds_write2_b32 v29, v60, v61 offset1:1
	ds_read2_b32 v[34:35], v14 offset0:33 offset1:41
	ds_read2_b32 v[36:37], v14 offset1:8
	ds_read2_b32 v[38:39], v14 offset0:66 offset1:74
	ds_read2_b32 v[40:41], v14 offset0:99 offset1:107
	ds_read2_b32 v[42:43], v14 offset0:132 offset1:140
	ds_read2_b32 v[44:45], v14 offset0:165 offset1:173
	ds_read2_b32 v[46:47], v14 offset0:198 offset1:206
	ds_read2_b32 v[48:49], v14 offset0:231 offset1:239
	v_lshl_add_u64 v[50:51], v[64:65], 0, v[62:63]
	s_waitcnt lgkmcnt(6)
	v_cvt_pk_bf16_f32 v30, v36, v34
	s_waitcnt lgkmcnt(4)
	v_cvt_pk_bf16_f32 v31, v38, v40
	s_waitcnt lgkmcnt(2)
	v_cvt_pk_bf16_f32 v32, v42, v44
	s_waitcnt lgkmcnt(0)
	v_cvt_pk_bf16_f32 v33, v46, v48
	global_store_dwordx4 v[50:51], v[30:33], off
	v_cvt_pk_bf16_f32 v34, v37, v35
	v_cvt_pk_bf16_f32 v35, v39, v41
	v_add_u32_e32 v30, s10, v11
	v_ashrrev_i32_e32 v31, 31, v30
	v_cvt_pk_bf16_f32 v36, v43, v45
	v_cvt_pk_bf16_f32 v37, v47, v49
	v_lshlrev_b64 v[30:31], 11, v[30:31]
	ds_read2_b32 v[38:39], v14 offset0:49 offset1:57
	ds_read2_b32 v[40:41], v14 offset0:16 offset1:24
	ds_read2_b32 v[42:43], v14 offset0:82 offset1:90
	ds_read2_b32 v[44:45], v14 offset0:115 offset1:123
	ds_read2_b32 v[46:47], v14 offset0:148 offset1:156
	ds_read2_b32 v[48:49], v14 offset0:181 offset1:189
	ds_read2_b32 v[50:51], v14 offset0:214 offset1:222
	ds_read2_b32 v[52:53], v14 offset0:247 offset1:255
	v_lshl_add_u64 v[30:31], v[64:65], 0, v[30:31]
	global_store_dwordx4 v[30:31], v[34:37], off
	s_waitcnt lgkmcnt(6)
	v_cvt_pk_bf16_f32 v30, v40, v38
	s_waitcnt lgkmcnt(4)
	v_cvt_pk_bf16_f32 v31, v42, v44
	v_add_u32_e32 v34, s10, v12
	v_ashrrev_i32_e32 v35, 31, v34
	v_lshlrev_b64 v[34:35], 11, v[34:35]
	s_waitcnt lgkmcnt(2)
	v_cvt_pk_bf16_f32 v32, v46, v48
	s_waitcnt lgkmcnt(0)
	v_cvt_pk_bf16_f32 v33, v50, v52
	v_lshl_add_u64 v[34:35], v[64:65], 0, v[34:35]
	global_store_dwordx4 v[34:35], v[30:33], off
	v_add_u32_e32 v34, s10, v13
	v_ashrrev_i32_e32 v35, 31, v34
	v_lshlrev_b64 v[34:35], 11, v[34:35]
	v_cvt_pk_bf16_f32 v30, v41, v39
	v_cvt_pk_bf16_f32 v31, v43, v45
	v_cvt_pk_bf16_f32 v32, v47, v49
	v_cvt_pk_bf16_f32 v33, v51, v53
	v_lshl_add_u64 v[34:35], v[64:65], 0, v[34:35]
	global_store_dwordx4 v[34:35], v[30:33], off
	s_branch .LBB0_280

.LBB0_1053:
	s_or_b64 exec, exec, s[28:29]
	v_lshl_add_u32 v33, v160, 2, s51
	ds_read_b128 v[36:39], v33
	ds_read_b128 v[40:43], v33 offset:32
	v_lshl_add_u32 v34, v65, 1, s36
	v_lshl_add_u32 v44, v162, 9, v34
	s_ff1_i32_b32 s28, s34
	s_waitcnt lgkmcnt(1)
	v_mul_f32_e32 v16, v16, v36
	v_bfe_u32 v45, v16, 16, 1
	v_add3_u32 v16, v16, v45, s37
	v_mul_f32_e32 v0, v0, v36
	ds_write_b16_d16_hi v44, v16
	v_bfe_u32 v16, v0, 16, 1
	v_add3_u32 v0, v0, v16, s37
	v_mul_f32_e32 v16, v17, v37
	v_bfe_u32 v17, v16, 16, 1
	ds_write_b16_d16_hi v44, v0 offset:64
	v_lshl_add_u32 v0, v160, 7, v34
	v_add3_u32 v16, v16, v17, s37
	v_mul_f32_e32 v1, v1, v37
	ds_write_b16_d16_hi v0, v16 offset:128
	v_bfe_u32 v16, v1, 16, 1
	v_add3_u32 v1, v1, v16, s37
	ds_write_b16_d16_hi v0, v1 offset:192
	v_mul_f32_e32 v1, v18, v38
	v_bfe_u32 v16, v1, 16, 1
	v_lshl_add_u32 v0, v161, 7, v34
	v_add3_u32 v1, v1, v16, s37
	ds_write_b16_d16_hi v0, v1
	v_mul_f32_e32 v1, v2, v38
	v_bfe_u32 v2, v1, 16, 1
	v_add3_u32 v1, v1, v2, s37
	ds_write_b16_d16_hi v0, v1 offset:64
	v_mul_f32_e32 v1, v19, v39
	v_bfe_u32 v2, v1, 16, 1
	v_lshl_add_u32 v0, v159, 7, v34
	v_add3_u32 v1, v1, v2, s37
	ds_write_b16_d16_hi v0, v1
	v_mul_f32_e32 v1, v3, v39
	v_bfe_u32 v2, v1, 16, 1
	v_add3_u32 v1, v1, v2, s37
	ds_write_b16_d16_hi v0, v1 offset:64
	s_waitcnt lgkmcnt(8)
	v_mul_f32_e32 v1, v20, v40
	v_bfe_u32 v2, v1, 16, 1
	v_lshl_add_u32 v0, v158, 7, v34
	v_add3_u32 v1, v1, v2, s37
	ds_write_b16_d16_hi v0, v1
	v_mul_f32_e32 v1, v4, v40
	v_bfe_u32 v2, v1, 16, 1
	v_add3_u32 v1, v1, v2, s37
	ds_write_b16_d16_hi v0, v1 offset:64
	v_mul_f32_e32 v1, v21, v41
	v_bfe_u32 v2, v1, 16, 1
	v_lshl_add_u32 v0, v157, 7, v34
	v_add3_u32 v1, v1, v2, s37
	ds_write_b16_d16_hi v0, v1
	v_mul_f32_e32 v1, v5, v41
	v_bfe_u32 v2, v1, 16, 1
	v_add3_u32 v1, v1, v2, s37
	ds_write_b16_d16_hi v0, v1 offset:64
	v_mul_f32_e32 v1, v22, v42
	v_bfe_u32 v2, v1, 16, 1
	v_lshl_add_u32 v0, v156, 7, v34
	v_add3_u32 v1, v1, v2, s37
	ds_write_b16_d16_hi v0, v1
	v_mul_f32_e32 v1, v6, v42
	v_bfe_u32 v2, v1, 16, 1
	v_add3_u32 v1, v1, v2, s37
	ds_write_b16_d16_hi v0, v1 offset:64
	v_mul_f32_e32 v0, v23, v43
	v_bfe_u32 v1, v0, 16, 1
	v_lshl_add_u32 v4, v155, 7, v34
	v_add3_u32 v0, v0, v1, s37
	ds_write_b16_d16_hi v4, v0
	ds_read_b128 v[0:3], v33 offset:64
	v_mul_f32_e32 v5, v7, v43
	v_bfe_u32 v6, v5, 16, 1
	v_add3_u32 v5, v5, v6, s37
	ds_write_b16_d16_hi v4, v5 offset:64
	ds_read_b128 v[4:7], v33 offset:96
	s_waitcnt lgkmcnt(2)
	v_mul_f32_e32 v17, v24, v0
	v_mul_f32_e32 v0, v8, v0
	v_bfe_u32 v18, v17, 16, 1
	v_bfe_u32 v8, v0, 16, 1
	v_lshl_add_u32 v16, v154, 7, v34
	v_add3_u32 v17, v17, v18, s37
	v_add3_u32 v0, v0, v8, s37
	v_mul_f32_e32 v8, v25, v1
	ds_write_b16_d16_hi v16, v17
	ds_write_b16_d16_hi v16, v0 offset:64
	v_bfe_u32 v16, v8, 16, 1
	v_lshl_add_u32 v0, v153, 7, v34
	v_add3_u32 v8, v8, v16, s37
	v_mul_f32_e32 v1, v9, v1
	ds_write_b16_d16_hi v0, v8
	v_bfe_u32 v8, v1, 16, 1
	v_add3_u32 v1, v1, v8, s37
	ds_write_b16_d16_hi v0, v1 offset:64
	v_mul_f32_e32 v1, v26, v2
	v_bfe_u32 v8, v1, 16, 1
	v_lshl_add_u32 v0, v152, 7, v34
	v_add3_u32 v1, v1, v8, s37
	ds_write_b16_d16_hi v0, v1
	v_mul_f32_e32 v1, v10, v2
	v_bfe_u32 v2, v1, 16, 1
	v_add3_u32 v1, v1, v2, s37
	ds_write_b16_d16_hi v0, v1 offset:64
	v_mul_f32_e32 v1, v27, v3
	v_bfe_u32 v2, v1, 16, 1
	v_lshl_add_u32 v0, v151, 7, v34
	v_add3_u32 v1, v1, v2, s37
	ds_write_b16_d16_hi v0, v1
	v_mul_f32_e32 v1, v11, v3
	v_bfe_u32 v2, v1, 16, 1
	v_add3_u32 v1, v1, v2, s37
	ds_write_b16_d16_hi v0, v1 offset:64
	s_waitcnt lgkmcnt(8)
	v_mul_f32_e32 v1, v28, v4
	v_bfe_u32 v2, v1, 16, 1
	v_lshl_add_u32 v0, v150, 7, v34
	v_add3_u32 v1, v1, v2, s37
	ds_write_b16_d16_hi v0, v1
	v_mul_f32_e32 v1, v12, v4
	v_bfe_u32 v2, v1, 16, 1
	v_add3_u32 v1, v1, v2, s37
	ds_write_b16_d16_hi v0, v1 offset:64
	v_mul_f32_e32 v1, v29, v5
	v_bfe_u32 v2, v1, 16, 1
	v_lshl_add_u32 v0, v149, 7, v34
	v_add3_u32 v1, v1, v2, s37
	ds_write_b16_d16_hi v0, v1
	v_mul_f32_e32 v1, v13, v5
	v_bfe_u32 v2, v1, 16, 1
	v_add3_u32 v1, v1, v2, s37
	ds_write_b16_d16_hi v0, v1 offset:64
	v_mul_f32_e32 v1, v30, v6
	v_bfe_u32 v2, v1, 16, 1
	v_lshl_add_u32 v0, v67, 7, v34
	v_add3_u32 v1, v1, v2, s37
	ds_write_b16_d16_hi v0, v1
	v_mul_f32_e32 v1, v14, v6
	v_bfe_u32 v2, v1, 16, 1
	v_add3_u32 v1, v1, v2, s37
	ds_write_b16_d16_hi v0, v1 offset:64
	v_mul_f32_e32 v1, v31, v7
	v_bfe_u32 v2, v1, 16, 1
	v_lshl_add_u32 v0, v66, 7, v34
	v_add3_u32 v1, v1, v2, s37
	ds_write_b16_d16_hi v0, v1
	v_mul_f32_e32 v1, v15, v7
	v_bfe_u32 v2, v1, 16, 1
	v_add3_u32 v1, v1, v2, s37
	ds_write_b16_d16_hi v0, v1 offset:64
	v_lshlrev_b32_e32 v0, 1, v32
	v_and_b32_e32 v0, 0x70, v0
	v_ashrrev_i32_e32 v8, 3, v148
	v_add_u32_e32 v16, s36, v0
	s_lshr_b32 s28, 0x800, s28
	v_mov_b32_e32 v1, v64
	s_mul_hi_u32 s29, s28, s13
	s_mul_i32 s28, s28, s13
	s_add_i32 s13, s19, s30
	v_lshl_add_u64 v[4:5], s[42:43], 0, v[0:1]
	v_lshl_add_u32 v0, v8, 7, v16
	v_or_b32_e32 v6, s11, v35
	s_add_u32 s28, s13, s28
	ds_read_b128 v[0:3], v0
	v_ashrrev_i32_e32 v7, 31, v6
	s_addc_u32 s29, 0, s29
	v_ashrrev_i32_e32 v9, 31, v8
	v_lshlrev_b64 v[6:7], 21, v[6:7]
	v_add_u32_e32 v14, 8, v8
	v_lshl_add_u64 v[10:11], s[28:29], 0, v[8:9]
	v_lshl_add_u64 v[12:13], v[4:5], 0, v[6:7]
	v_lshl_add_u32 v4, v14, 7, v16
	v_lshlrev_b64 v[10:11], 7, v[10:11]
	ds_read_b128 v[4:7], v4
	v_lshl_add_u64 v[10:11], v[12:13], 0, v[10:11]
	v_ashrrev_i32_e32 v15, 31, v14
	s_waitcnt lgkmcnt(1)
	global_store_dwordx4 v[10:11], v[0:3], off
	v_readlane_b32 s11, v254, 27
	s_waitcnt vmcnt(1)
	v_mov_b64_e32 v[134:135], v[130:131]
	v_lshl_add_u64 v[0:1], s[28:29], 0, v[14:15]
	v_lshlrev_b64 v[0:1], 7, v[0:1]
	v_lshl_add_u64 v[0:1], v[12:13], 0, v[0:1]
	s_waitcnt lgkmcnt(0)
	global_store_dwordx4 v[0:1], v[4:7], off
	v_mov_b64_e32 v[138:139], v[126:127]
	v_mov_b64_e32 v[142:143], v[122:123]
	v_add_u32_e32 v4, 16, v8
	v_lshl_add_u32 v0, v4, 7, v16
	v_ashrrev_i32_e32 v5, 31, v4
	ds_read_b128 v[0:3], v0
	v_lshl_add_u64 v[4:5], s[28:29], 0, v[4:5]
	v_lshlrev_b64 v[4:5], 7, v[4:5]
	v_add_u32_e32 v8, 24, v8
	v_lshl_add_u64 v[10:11], v[12:13], 0, v[4:5]
	v_lshl_add_u32 v4, v8, 7, v16
	ds_read_b128 v[4:7], v4
	v_ashrrev_i32_e32 v9, 31, v8
	s_waitcnt lgkmcnt(1)
	global_store_dwordx4 v[10:11], v[0:3], off
	v_mov_b64_e32 v[146:147], v[118:119]
	s_add_i32 s5, s5, s11
	v_lshl_add_u64 v[0:1], s[28:29], 0, v[8:9]
	v_lshlrev_b64 v[0:1], 7, v[0:1]
	v_lshl_add_u64 v[0:1], v[12:13], 0, v[0:1]
	s_waitcnt lgkmcnt(0)
	global_store_dwordx4 v[0:1], v[4:7], off
	s_add_i32 s4, s4, s96
	s_andn2_b64 vcc, exec, s[44:45]
	v_mov_b64_e32 v[132:133], v[128:129]
	v_mov_b64_e32 v[136:137], v[124:125]
	v_mov_b64_e32 v[140:141], v[120:121]
	v_mov_b64_e32 v[144:145], v[116:117]
	s_mov_b32 s11, s10
	s_barrier
	s_cbranch_vccz .LBB0_1121
